# speedup vs baseline: 1.0215x; 1.0143x over previous
; #define PG8_STAGE(bufoff, gbase, voff) do { _Pragma("unroll") for (int _i = 0; _i < 2; ++_i) \
;         __builtin_amdgcn_global_load_lds((const unsigned*)((const char*)(gbase) + (voff)[_i]), (LAS unsigned*)(lds + (bufoff) + ldsw + _i * 8192), 16, 0, 0); } while (0)
; #define PG8_LDA(dst, b, h) do { _Pragma("unroll") for (int m = 0; m < 4; ++m) _Pragma("unroll") for (int k = 0; k < 2; ++k) dst[m][k] = *(const LAS bf16x8*)(lds + PG8_SA(b, h) + aoff + m * 2048 + k * 1024); } while (0)
; #define PG8_LDB(dst, b, h) do { _Pragma("unroll") for (int n = 0; n < 2; ++n) _Pragma("unroll") for (int k = 0; k < 2; ++k) dst[n][k] = *(const LAS bf16x8*)(lds + PG8_SB(b, h) + boff + n * 2048 + k * 1024); } while (0)
; #define PG8_BAR __builtin_amdgcn_s_barrier()
; template <class Epi, class Pre, bool AG = false>
; __device__ __forceinline__ void gemm_phase(LAS unsigned char* lds, const Gemm g, const StaticOrder& S, const Epi& E, const Pre& P) {
;     ...
;         const bool has_next = S.next(ui + 1, nxt);
;         const char* nA = has_next ? (const char*)g.A + (size_t)nxt.pm * tstepA : cA; const char* nB = has_next ? (const char*)g.Bt + (size_t)nxt.pn * tstep : cB;
;         for (int t = 0; t < nt; t += 2) {
;             const bool last = (t == nt - 2);
;             const char* a1 = cA + (size_t)(t + 1) * kstepA;
;             const char* a2 = last ? nA : cA + (size_t)(t + 2) * kstepA; const char* b2 = last ? nB : cB + (size_t)(t + 2) * kstep;
;             const char* a3 = a2 + kstepA; const char* b3 = b2 + kstep;
;             if constexpr (Epi::MIDK) { if (t == E.midk_t) E.mid(acc, cur, ui, wr, wc, fr, fq); }
;             PG8_LDB(B0, 0, 0); PG8_LDB(B1, 0, 1); PG8_SCHED; PG8_LDA(At, 0, 0); PG8_STAGE(PG8_SA(1, 1), a1 + hstepA, voffA);
;             PG8_WAIT_V(8); PG8_WAIT_L(0); PG8_BAR; PG8_MMA(0, 0, At, B0); PG8_MMA(0, 1, At, B1); PG8_BAR; PG8_SCHED;
;             PG8_LDA(At, 0, 1); PG8_STAGE(PG8_SB(0, 0), b2, voffB); PG8_STAGE(PG8_SB(0, 1), b2 + hstep, voffB); PG8_STAGE(PG8_SA(0, 0), a2, voffA);
;             PG8_WAIT_V(8); PG8_WAIT_L(0); PG8_BAR; PG8_MMA(1, 0, At, B0); PG8_MMA(1, 1, At, B1); PG8_BAR; PG8_SCHED;
;             PG8_LDB(B0, 1, 0); PG8_LDB(B1, 1, 1); PG8_SCHED; PG8_LDA(At, 1, 0); PG8_STAGE(PG8_SA(0, 1), a2 + hstepA, voffA);
;             PG8_WAIT_V(8); PG8_WAIT_L(0); PG8_BAR; PG8_MMA(0, 0, At, B0); PG8_MMA(0, 1, At, B1); PG8_BAR; PG8_SCHED;
.LBB0_211:
	s_ashr_i32 s27, s26, 31
	s_lshl_b64 s[12:13], s[26:27], 19
	s_add_u32 s28, s20, s12
	s_addc_u32 s29, s24, s13
	s_and_b64 s[12:13], s[6:7], exec
	s_cselect_b32 s12, s29, s45
	s_cselect_b32 s13, s28, s44
	s_ashr_i32 s17, s16, 31
	s_lshl_b64 s[42:43], s[16:17], 19
	s_add_u32 s42, s25, s42
	s_addc_u32 s43, s30, s43
	s_and_b64 s[54:55], s[6:7], exec
	s_cselect_b32 s17, s43, s47
	s_cselect_b32 s27, s42, s46
	s_add_u32 s44, s44, 0x40080
	s_addc_u32 s45, s45, 0
	s_add_u32 s76, s46, 0x100
	s_addc_u32 s77, s47, 0
	s_mov_b32 s79, -2
	s_add_u32 s46, s44, 0xfffc0080
	s_addc_u32 s47, s45, -1
	s_add_i32 s84, 0, 0x10000
	s_cmp_eq_u32 s79, 12
	s_cselect_b32 s55, s12, s47
	s_cselect_b32 s54, s13, s46
	s_cselect_b32 s47, s17, s77
	s_cselect_b32 s46, s27, s76
	s_add_i32 s86, 0, 0x14000
	v_add_u32_e32 v154, s84, v148
	v_add_u32_e32 v170, s86, v148
	ds_read_b128 v[140:143], v154
	ds_read_b128 v[144:147], v154 offset:1024
	ds_read_b128 v[150:153], v154 offset:2048
	ds_read_b128 v[154:157], v154 offset:3072
	ds_read_b128 v[158:161], v170
	ds_read_b128 v[162:165], v170 offset:1024
	ds_read_b128 v[166:169], v170 offset:2048
	ds_read_b128 v[170:173], v170 offset:3072
	v_lshl_add_u64 v[178:179], s[44:45], 0, v[0:1]
	s_add_i32 m0, s38, 0xc000
	ds_read_b128 v[174:177], v149
	ds_read_b128 v[194:197], v149 offset:1024
	ds_read_b128 v[198:201], v149 offset:2048
	ds_read_b128 v[202:205], v149 offset:3072
	ds_read_b128 v[206:209], v149 offset:4096
	ds_read_b128 v[210:213], v149 offset:5120
	ds_read_b128 v[214:217], v149 offset:6144
	ds_read_b128 v[218:221], v149 offset:7168
	global_load_lds_dwordx4 v[178:179], off
	v_lshl_add_u64 v[178:179], s[44:45], 0, v[138:139]
	s_add_i32 m0, s38, 0xe000
	s_nop 0
	global_load_lds_dwordx4 v[178:179], off
	s_waitcnt vmcnt(8)
	s_waitcnt lgkmcnt(0)
	s_barrier
	s_setprio 1
	s_waitcnt lgkmcnt(0)
	v_mfma_f32_16x16x32_bf16 v[122:125], v[140:143], v[174:177], 0
	v_mfma_f32_16x16x32_bf16 v[114:117], v[150:153], v[174:177], 0
	v_mfma_f32_16x16x32_bf16 v[106:109], v[140:143], v[198:201], 0
	v_mfma_f32_16x16x32_bf16 v[98:101], v[150:153], v[198:201], 0
	v_mfma_f32_16x16x32_bf16 v[90:93], v[140:143], v[206:209], 0
	v_mfma_f32_16x16x32_bf16 v[82:85], v[150:153], v[206:209], 0
	v_mfma_f32_16x16x32_bf16 v[74:77], v[140:143], v[214:217], 0
	v_mfma_f32_16x16x32_bf16 v[66:69], v[150:153], v[214:217], 0
	v_mfma_f32_16x16x32_bf16 v[122:125], v[144:147], v[194:197], v[122:125]
	v_mfma_f32_16x16x32_bf16 v[114:117], v[154:157], v[194:197], v[114:117]
	v_mfma_f32_16x16x32_bf16 v[106:109], v[144:147], v[202:205], v[106:109]
	v_mfma_f32_16x16x32_bf16 v[98:101], v[154:157], v[202:205], v[98:101]
	v_mfma_f32_16x16x32_bf16 v[90:93], v[144:147], v[210:213], v[90:93]
	v_mfma_f32_16x16x32_bf16 v[82:85], v[154:157], v[210:213], v[82:85]
	v_mfma_f32_16x16x32_bf16 v[74:77], v[144:147], v[218:221], v[74:77]
	v_mfma_f32_16x16x32_bf16 v[66:69], v[154:157], v[218:221], v[66:69]
	s_setprio 0
	s_setprio 1
	v_mfma_f32_16x16x32_bf16 v[126:129], v[158:161], v[174:177], 0
	v_mfma_f32_16x16x32_bf16 v[118:121], v[166:169], v[174:177], 0
	v_mfma_f32_16x16x32_bf16 v[110:113], v[158:161], v[198:201], 0
	v_mfma_f32_16x16x32_bf16 v[102:105], v[166:169], v[198:201], 0
	v_mfma_f32_16x16x32_bf16 v[94:97], v[158:161], v[206:209], 0
	v_mfma_f32_16x16x32_bf16 v[86:89], v[166:169], v[206:209], 0
	v_mfma_f32_16x16x32_bf16 v[78:81], v[158:161], v[214:217], 0
	v_mfma_f32_16x16x32_bf16 v[70:73], v[166:169], v[214:217], 0
	v_mfma_f32_16x16x32_bf16 v[126:129], v[162:165], v[194:197], v[126:129]
	v_mfma_f32_16x16x32_bf16 v[118:121], v[170:173], v[194:197], v[118:121]
	v_mfma_f32_16x16x32_bf16 v[110:113], v[162:165], v[202:205], v[110:113]
	v_mfma_f32_16x16x32_bf16 v[102:105], v[170:173], v[202:205], v[102:105]
	v_mfma_f32_16x16x32_bf16 v[94:97], v[162:165], v[210:213], v[94:97]
	v_mfma_f32_16x16x32_bf16 v[86:89], v[170:173], v[210:213], v[86:89]
	v_mfma_f32_16x16x32_bf16 v[78:81], v[162:165], v[218:221], v[78:81]
	v_mfma_f32_16x16x32_bf16 v[70:73], v[170:173], v[218:221], v[70:73]
	s_setprio 0
	s_barrier
	s_add_i32 s84, s84, s31
	v_lshl_add_u64 v[178:179], s[46:47], 0, v[134:135]
	s_mov_b32 m0, s84
	ds_read_b128 v[174:177], v149 offset:16384
	ds_read_b128 v[194:197], v149 offset:17408
	ds_read_b128 v[198:201], v149 offset:18432
	ds_read_b128 v[202:205], v149 offset:19456
	ds_read_b128 v[206:209], v149 offset:20480
	ds_read_b128 v[210:213], v149 offset:21504
	ds_read_b128 v[214:217], v149 offset:22528
	ds_read_b128 v[218:221], v149 offset:23552
	global_load_lds_dwordx4 v[178:179], off
	s_add_i32 m0, s84, 0x2000
	s_add_u32 s84, s46, 0x40000
	v_lshl_add_u64 v[180:181], s[46:47], 0, v[130:131]
	s_addc_u32 s85, s47, 0
	s_add_i32 s86, s86, s31
	global_load_lds_dwordx4 v[180:181], off
	v_lshl_add_u64 v[182:183], s[84:85], 0, v[134:135]
	s_mov_b32 m0, s86
	v_lshl_add_u64 v[188:189], s[54:55], 0, v[132:133]
	global_load_lds_dwordx4 v[182:183], off
	v_lshl_add_u64 v[182:183], s[84:85], 0, v[130:131]
	s_add_i32 m0, s86, 0x2000
	s_nop 0
	global_load_lds_dwordx4 v[182:183], off
	v_lshl_add_u64 v[182:183], s[54:55], 0, v[136:137]
	s_mov_b32 m0, s38
	s_nop 0
	global_load_lds_dwordx4 v[182:183], off
	s_mov_b32 m0, s48
	s_nop 0
	global_load_lds_dwordx4 v[188:189], off
	s_waitcnt vmcnt(8)
	s_waitcnt lgkmcnt(0)
	s_barrier
; #define PG8_STAGE(bufoff, gbase, voff) do { _Pragma("unroll") for (int _i = 0; _i < 2; ++_i) \
;         __builtin_amdgcn_global_load_lds((const unsigned*)((const char*)(gbase) + (voff)[_i]), (LAS unsigned*)(lds + (bufoff) + ldsw + _i * 8192), 16, 0, 0); } while (0)
; #define PG8_LDA(dst, b, h) do { _Pragma("unroll") for (int m = 0; m < 4; ++m) _Pragma("unroll") for (int k = 0; k < 2; ++k) dst[m][k] = *(const LAS bf16x8*)(lds + PG8_SA(b, h) + aoff + m * 2048 + k * 1024); } while (0)
; #define PG8_LDB(dst, b, h) do { _Pragma("unroll") for (int n = 0; n < 2; ++n) _Pragma("unroll") for (int k = 0; k < 2; ++k) dst[n][k] = *(const LAS bf16x8*)(lds + PG8_SB(b, h) + boff + n * 2048 + k * 1024); } while (0)
; #define PG8_MMA(ai, bj, At, Bt) do { __builtin_amdgcn_s_setprio(1); _Pragma("unroll") for (int m = 0; m < 4; ++m) _Pragma("unroll") for (int n = 0; n < 2; ++n) _Pragma("unroll") for (int k = 0; k < 2; ++k) \
;         acc[ai][bj][m][n] = __builtin_amdgcn_mfma_f32_16x16x32_bf16(Bt[n][k], At[m][k], acc[ai][bj][m][n], 0, 0, 0); __builtin_amdgcn_s_setprio(0); } while (0)
; #define PG8_WAIT_V(n) asm volatile("s_waitcnt vmcnt(" #n ")" ::: "memory")
; template <class Epi, class Pre, bool AG = false>
; __device__ __forceinline__ void gemm_phase(LAS unsigned char* lds, const Gemm g, const StaticOrder& S, const Epi& E, const Pre& P) {
;     ...
;             PG8_LDB(B0, 0, 0); PG8_LDB(B1, 0, 1); PG8_SCHED; PG8_LDA(At, 0, 0); PG8_STAGE(PG8_SA(1, 1), a1 + hstepA, voffA);
;             PG8_WAIT_V(8); PG8_WAIT_L(0); PG8_BAR; PG8_MMA(0, 0, At, B0); PG8_MMA(0, 1, At, B1); PG8_BAR; PG8_SCHED;
;             PG8_LDA(At, 0, 1); PG8_STAGE(PG8_SB(0, 0), b2, voffB); PG8_STAGE(PG8_SB(0, 1), b2 + hstep, voffB); PG8_STAGE(PG8_SA(0, 0), a2, voffA);
;             PG8_WAIT_V(8); PG8_WAIT_L(0); PG8_BAR; PG8_MMA(1, 0, At, B0); PG8_MMA(1, 1, At, B1); PG8_BAR; PG8_SCHED;
;             PG8_LDB(B0, 1, 0); PG8_LDB(B1, 1, 1); PG8_SCHED; PG8_LDA(At, 1, 0); PG8_STAGE(PG8_SA(0, 1), a2 + hstepA, voffA);
;             PG8_WAIT_V(8); PG8_WAIT_L(0); PG8_BAR; PG8_MMA(0, 0, At, B0); PG8_MMA(0, 1, At, B1); PG8_BAR; PG8_SCHED;
;             PG8_LDA(At, 1, 1); PG8_STAGE(PG8_SB(1, 0), b3, voffB); PG8_STAGE(PG8_SB(1, 1), b3 + hstep, voffB); PG8_STAGE(PG8_SA(1, 0), a3, voffA);
;             PG8_WAIT_V(8); PG8_WAIT_L(0); PG8_BAR; PG8_MMA(1, 0, At, B0); PG8_MMA(1, 1, At, B1); PG8_BAR; PG8_SCHED;
	s_setprio 1
	s_waitcnt lgkmcnt(0)
	v_mfma_f32_16x16x32_bf16 v[58:61], v[140:143], v[174:177], 0
	v_mfma_f32_16x16x32_bf16 v[50:53], v[150:153], v[174:177], 0
	v_mfma_f32_16x16x32_bf16 v[42:45], v[140:143], v[198:201], 0
	v_mfma_f32_16x16x32_bf16 v[34:37], v[150:153], v[198:201], 0
	v_mfma_f32_16x16x32_bf16 v[26:29], v[140:143], v[206:209], 0
	v_mfma_f32_16x16x32_bf16 v[18:21], v[150:153], v[206:209], 0
	v_mfma_f32_16x16x32_bf16 v[10:13], v[140:143], v[214:217], 0
	v_mfma_f32_16x16x32_bf16 v[6:9], v[150:153], v[214:217], 0
	v_mfma_f32_16x16x32_bf16 v[58:61], v[144:147], v[194:197], v[58:61]
	v_mfma_f32_16x16x32_bf16 v[50:53], v[154:157], v[194:197], v[50:53]
	v_mfma_f32_16x16x32_bf16 v[42:45], v[144:147], v[202:205], v[42:45]
	v_mfma_f32_16x16x32_bf16 v[34:37], v[154:157], v[202:205], v[34:37]
	v_mfma_f32_16x16x32_bf16 v[26:29], v[144:147], v[210:213], v[26:29]
	v_mfma_f32_16x16x32_bf16 v[18:21], v[154:157], v[210:213], v[18:21]
	v_mfma_f32_16x16x32_bf16 v[10:13], v[144:147], v[218:221], v[10:13]
	v_mfma_f32_16x16x32_bf16 v[6:9], v[154:157], v[218:221], v[6:9]
	s_setprio 0
	s_setprio 1
	v_mfma_f32_16x16x32_bf16 v[62:65], v[158:161], v[174:177], 0
	v_mfma_f32_16x16x32_bf16 v[54:57], v[166:169], v[174:177], 0
	v_mfma_f32_16x16x32_bf16 v[46:49], v[158:161], v[198:201], 0
	v_mfma_f32_16x16x32_bf16 v[38:41], v[166:169], v[198:201], 0
	v_mfma_f32_16x16x32_bf16 v[30:33], v[158:161], v[206:209], 0
	v_mfma_f32_16x16x32_bf16 v[22:25], v[166:169], v[206:209], 0
	v_mfma_f32_16x16x32_bf16 v[14:17], v[158:161], v[214:217], 0
	v_mfma_f32_16x16x32_bf16 v[2:5], v[166:169], v[214:217], 0
	v_mfma_f32_16x16x32_bf16 v[62:65], v[162:165], v[194:197], v[62:65]
	v_mfma_f32_16x16x32_bf16 v[54:57], v[170:173], v[194:197], v[54:57]
	v_mfma_f32_16x16x32_bf16 v[46:49], v[162:165], v[202:205], v[46:49]
	v_mfma_f32_16x16x32_bf16 v[38:41], v[170:173], v[202:205], v[38:41]
	v_mfma_f32_16x16x32_bf16 v[30:33], v[162:165], v[210:213], v[30:33]
	v_mfma_f32_16x16x32_bf16 v[22:25], v[170:173], v[210:213], v[22:25]
	v_mfma_f32_16x16x32_bf16 v[14:17], v[162:165], v[218:221], v[14:17]
	v_mfma_f32_16x16x32_bf16 v[2:5], v[170:173], v[218:221], v[2:5]
	s_setprio 0
	s_barrier
	s_add_i32 s84, 0, 0x18000
	s_add_i32 s85, 0, 0x1c000
	v_add_u32_e32 v154, s84, v148
	v_add_u32_e32 v170, s85, v148
	ds_read_b128 v[140:143], v154
	ds_read_b128 v[144:147], v154 offset:1024
	ds_read_b128 v[150:153], v154 offset:2048
	ds_read_b128 v[154:157], v154 offset:3072
	ds_read_b128 v[158:161], v170
	ds_read_b128 v[162:165], v170 offset:1024
	ds_read_b128 v[166:169], v170 offset:2048
	ds_read_b128 v[170:173], v170 offset:3072
	s_add_u32 s54, s54, 0x40000
	s_addc_u32 s55, s55, 0
	s_mov_b32 m0, s49
	v_lshl_add_u64 v[190:191], s[54:55], 0, v[136:137]
	ds_read_b128 v[174:177], v149 offset:32768
	ds_read_b128 v[194:197], v149 offset:33792
	ds_read_b128 v[198:201], v149 offset:34816
	ds_read_b128 v[202:205], v149 offset:35840
	ds_read_b128 v[206:209], v149 offset:36864
	ds_read_b128 v[210:213], v149 offset:37888
	ds_read_b128 v[214:217], v149 offset:38912
	ds_read_b128 v[218:221], v149 offset:39936
	global_load_lds_dwordx4 v[190:191], off
	v_lshl_add_u64 v[190:191], s[54:55], 0, v[132:133]
	s_mov_b32 m0, s53
	s_nop 0
	global_load_lds_dwordx4 v[190:191], off
	s_waitcnt vmcnt(8)
	s_waitcnt lgkmcnt(0)
	s_barrier
	s_setprio 1
	s_waitcnt lgkmcnt(0)
	v_mfma_f32_16x16x32_bf16 v[122:125], v[140:143], v[174:177], v[122:125]
	v_mfma_f32_16x16x32_bf16 v[114:117], v[150:153], v[174:177], v[114:117]
	v_mfma_f32_16x16x32_bf16 v[106:109], v[140:143], v[198:201], v[106:109]
	v_mfma_f32_16x16x32_bf16 v[98:101], v[150:153], v[198:201], v[98:101]
	v_mfma_f32_16x16x32_bf16 v[90:93], v[140:143], v[206:209], v[90:93]
	v_mfma_f32_16x16x32_bf16 v[82:85], v[150:153], v[206:209], v[82:85]
	v_mfma_f32_16x16x32_bf16 v[74:77], v[140:143], v[214:217], v[74:77]
	v_mfma_f32_16x16x32_bf16 v[66:69], v[150:153], v[214:217], v[66:69]
	v_mfma_f32_16x16x32_bf16 v[122:125], v[144:147], v[194:197], v[122:125]
	v_mfma_f32_16x16x32_bf16 v[114:117], v[154:157], v[194:197], v[114:117]
	v_mfma_f32_16x16x32_bf16 v[106:109], v[144:147], v[202:205], v[106:109]
	v_mfma_f32_16x16x32_bf16 v[98:101], v[154:157], v[202:205], v[98:101]
	v_mfma_f32_16x16x32_bf16 v[90:93], v[144:147], v[210:213], v[90:93]
	v_mfma_f32_16x16x32_bf16 v[82:85], v[154:157], v[210:213], v[82:85]
	v_mfma_f32_16x16x32_bf16 v[74:77], v[144:147], v[218:221], v[74:77]
	v_mfma_f32_16x16x32_bf16 v[66:69], v[154:157], v[218:221], v[66:69]
	s_setprio 0
	s_setprio 1
	v_mfma_f32_16x16x32_bf16 v[126:129], v[158:161], v[174:177], v[126:129]
	v_mfma_f32_16x16x32_bf16 v[118:121], v[166:169], v[174:177], v[118:121]
	v_mfma_f32_16x16x32_bf16 v[110:113], v[158:161], v[198:201], v[110:113]
	v_mfma_f32_16x16x32_bf16 v[102:105], v[166:169], v[198:201], v[102:105]
	v_mfma_f32_16x16x32_bf16 v[94:97], v[158:161], v[206:209], v[94:97]
	v_mfma_f32_16x16x32_bf16 v[86:89], v[166:169], v[206:209], v[86:89]
	v_mfma_f32_16x16x32_bf16 v[78:81], v[158:161], v[214:217], v[78:81]
	v_mfma_f32_16x16x32_bf16 v[70:73], v[166:169], v[214:217], v[70:73]
	v_mfma_f32_16x16x32_bf16 v[126:129], v[162:165], v[194:197], v[126:129]
	v_mfma_f32_16x16x32_bf16 v[118:121], v[170:173], v[194:197], v[118:121]
	v_mfma_f32_16x16x32_bf16 v[110:113], v[162:165], v[202:205], v[110:113]
	v_mfma_f32_16x16x32_bf16 v[102:105], v[170:173], v[202:205], v[102:105]
	v_mfma_f32_16x16x32_bf16 v[94:97], v[162:165], v[210:213], v[94:97]
	v_mfma_f32_16x16x32_bf16 v[86:89], v[170:173], v[210:213], v[86:89]
	v_mfma_f32_16x16x32_bf16 v[78:81], v[162:165], v[218:221], v[78:81]
	v_mfma_f32_16x16x32_bf16 v[70:73], v[170:173], v[218:221], v[70:73]
	s_setprio 0
	s_barrier
; #define PG8_STAGE(bufoff, gbase, voff) do { _Pragma("unroll") for (int _i = 0; _i < 2; ++_i) \
;         __builtin_amdgcn_global_load_lds((const unsigned*)((const char*)(gbase) + (voff)[_i]), (LAS unsigned*)(lds + (bufoff) + ldsw + _i * 8192), 16, 0, 0); } while (0)
; #define PG8_LDA(dst, b, h) do { _Pragma("unroll") for (int m = 0; m < 4; ++m) _Pragma("unroll") for (int k = 0; k < 2; ++k) dst[m][k] = *(const LAS bf16x8*)(lds + PG8_SA(b, h) + aoff + m * 2048 + k * 1024); } while (0)
; #define PG8_LDB(dst, b, h) do { _Pragma("unroll") for (int n = 0; n < 2; ++n) _Pragma("unroll") for (int k = 0; k < 2; ++k) dst[n][k] = *(const LAS bf16x8*)(lds + PG8_SB(b, h) + boff + n * 2048 + k * 1024); } while (0)
; #define PG8_MMA(ai, bj, At, Bt) do { __builtin_amdgcn_s_setprio(1); _Pragma("unroll") for (int m = 0; m < 4; ++m) _Pragma("unroll") for (int n = 0; n < 2; ++n) _Pragma("unroll") for (int k = 0; k < 2; ++k) \
;         acc[ai][bj][m][n] = __builtin_amdgcn_mfma_f32_16x16x32_bf16(Bt[n][k], At[m][k], acc[ai][bj][m][n], 0, 0, 0); __builtin_amdgcn_s_setprio(0); } while (0)
; #define PG8_WAIT_V(n) asm volatile("s_waitcnt vmcnt(" #n ")" ::: "memory")
; #define PG8_WAIT_L(n) asm volatile("s_waitcnt lgkmcnt(" #n ")" ::: "memory")
; #define PG8_BAR __builtin_amdgcn_s_barrier()
; #define PG8_SCHED __builtin_amdgcn_sched_barrier(0)
; template <class Epi, class Pre, bool AG = false>
; __device__ __forceinline__ void gemm_phase(LAS unsigned char* lds, const Gemm g, const StaticOrder& S, const Epi& E, const Pre& P) {
;     ...
;             PG8_LDB(B0, 1, 0); PG8_LDB(B1, 1, 1); PG8_SCHED; PG8_LDA(At, 1, 0); PG8_STAGE(PG8_SA(0, 1), a2 + hstepA, voffA);
;             PG8_WAIT_V(8); PG8_WAIT_L(0); PG8_BAR; PG8_MMA(0, 0, At, B0); PG8_MMA(0, 1, At, B1); PG8_BAR; PG8_SCHED;
;             PG8_LDA(At, 1, 1); PG8_STAGE(PG8_SB(1, 0), b3, voffB); PG8_STAGE(PG8_SB(1, 1), b3 + hstep, voffB); PG8_STAGE(PG8_SA(1, 0), a3, voffA);
;             PG8_WAIT_V(8); PG8_WAIT_L(0); PG8_BAR; PG8_MMA(1, 0, At, B0); PG8_MMA(1, 1, At, B1); PG8_BAR; PG8_SCHED;
;         }
	s_add_i32 s54, s84, s31
	v_lshl_add_u64 v[178:179], v[178:179], 0, s[66:67]
	s_mov_b32 m0, s54
	ds_read_b128 v[174:177], v149 offset:49152
	ds_read_b128 v[194:197], v149 offset:50176
	ds_read_b128 v[198:201], v149 offset:51200
	ds_read_b128 v[202:205], v149 offset:52224
	ds_read_b128 v[206:209], v149 offset:53248
	ds_read_b128 v[210:213], v149 offset:54272
	ds_read_b128 v[214:217], v149 offset:55296
	ds_read_b128 v[218:221], v149 offset:56320
	global_load_lds_dwordx4 v[178:179], off
	s_add_i32 m0, s54, 0x2000
	s_add_u32 s46, s46, 0x40080
	v_lshl_add_u64 v[178:179], v[180:181], 0, s[66:67]
	s_addc_u32 s47, s47, 0
	s_add_i32 s54, s85, s31
	global_load_lds_dwordx4 v[178:179], off
	v_lshl_add_u64 v[178:179], s[46:47], 0, v[134:135]
	s_mov_b32 m0, s54
	s_nop 0
	global_load_lds_dwordx4 v[178:179], off
	v_lshl_add_u64 v[178:179], s[46:47], 0, v[130:131]
	s_add_i32 m0, s54, 0x2000
	s_nop 0
	global_load_lds_dwordx4 v[178:179], off
	v_lshl_add_u64 v[178:179], v[182:183], 0, s[66:67]
	s_mov_b32 m0, s58
	s_nop 0
	global_load_lds_dwordx4 v[178:179], off
	v_lshl_add_u64 v[178:179], v[188:189], 0, s[66:67]
	s_mov_b32 m0, s59
	s_nop 0
	global_load_lds_dwordx4 v[178:179], off
	s_waitcnt vmcnt(8)
	s_waitcnt lgkmcnt(0)
	s_barrier
	s_setprio 1
	s_waitcnt lgkmcnt(0)
	v_mfma_f32_16x16x32_bf16 v[58:61], v[140:143], v[174:177], v[58:61]
	v_mfma_f32_16x16x32_bf16 v[50:53], v[150:153], v[174:177], v[50:53]
	v_mfma_f32_16x16x32_bf16 v[42:45], v[140:143], v[198:201], v[42:45]
	v_mfma_f32_16x16x32_bf16 v[34:37], v[150:153], v[198:201], v[34:37]
	v_mfma_f32_16x16x32_bf16 v[26:29], v[140:143], v[206:209], v[26:29]
	v_mfma_f32_16x16x32_bf16 v[18:21], v[150:153], v[206:209], v[18:21]
	v_mfma_f32_16x16x32_bf16 v[10:13], v[140:143], v[214:217], v[10:13]
	v_mfma_f32_16x16x32_bf16 v[6:9], v[150:153], v[214:217], v[6:9]
	v_mfma_f32_16x16x32_bf16 v[58:61], v[144:147], v[194:197], v[58:61]
	v_mfma_f32_16x16x32_bf16 v[50:53], v[154:157], v[194:197], v[50:53]
	v_mfma_f32_16x16x32_bf16 v[42:45], v[144:147], v[202:205], v[42:45]
	v_mfma_f32_16x16x32_bf16 v[34:37], v[154:157], v[202:205], v[34:37]
	v_mfma_f32_16x16x32_bf16 v[26:29], v[144:147], v[210:213], v[26:29]
	v_mfma_f32_16x16x32_bf16 v[18:21], v[154:157], v[210:213], v[18:21]
	v_mfma_f32_16x16x32_bf16 v[10:13], v[144:147], v[218:221], v[10:13]
	v_mfma_f32_16x16x32_bf16 v[6:9], v[154:157], v[218:221], v[6:9]
	s_setprio 0
	s_setprio 1
	v_mfma_f32_16x16x32_bf16 v[62:65], v[158:161], v[174:177], v[62:65]
	v_mfma_f32_16x16x32_bf16 v[54:57], v[166:169], v[174:177], v[54:57]
	v_mfma_f32_16x16x32_bf16 v[46:49], v[158:161], v[198:201], v[46:49]
	v_mfma_f32_16x16x32_bf16 v[38:41], v[166:169], v[198:201], v[38:41]
	v_mfma_f32_16x16x32_bf16 v[30:33], v[158:161], v[206:209], v[30:33]
	v_mfma_f32_16x16x32_bf16 v[22:25], v[166:169], v[206:209], v[22:25]
	v_mfma_f32_16x16x32_bf16 v[14:17], v[158:161], v[214:217], v[14:17]
	v_mfma_f32_16x16x32_bf16 v[2:5], v[166:169], v[214:217], v[2:5]
	v_mfma_f32_16x16x32_bf16 v[62:65], v[162:165], v[194:197], v[62:65]
	v_mfma_f32_16x16x32_bf16 v[54:57], v[170:173], v[194:197], v[54:57]
	v_mfma_f32_16x16x32_bf16 v[46:49], v[162:165], v[202:205], v[46:49]
	v_mfma_f32_16x16x32_bf16 v[38:41], v[170:173], v[202:205], v[38:41]
	v_mfma_f32_16x16x32_bf16 v[30:33], v[162:165], v[210:213], v[30:33]
	v_mfma_f32_16x16x32_bf16 v[22:25], v[170:173], v[210:213], v[22:25]
	v_mfma_f32_16x16x32_bf16 v[14:17], v[162:165], v[218:221], v[14:17]
	v_mfma_f32_16x16x32_bf16 v[2:5], v[170:173], v[218:221], v[2:5]
	s_setprio 0
	s_barrier
	s_add_i32 s79, s79, 2
	s_add_u32 s44, s44, 0x100
	s_addc_u32 s45, s45, 0
	s_add_u32 s76, s76, 0x100
	s_addc_u32 s77, s77, 0
	s_cmp_gt_u32 s79, 13
	s_cbranch_scc0 .LBB0_212
	s_branch .Lpeel_gu_after

; __device__ __forceinline__ unsigned pk2(float lo, float hi) { unsigned r; asm("v_cvt_pk_bf16_f32 %0, %1, %2" : "=v"(r) : "v"(lo), "v"(hi)); return r; }
; __device__ __forceinline__ void st16_wt(void* p, u32x4 v) { asm volatile("global_store_dwordx4 %0, %1, off sc1\n\ts_nop 1" :: "v"(p), "v"(v) : "memory"); }
;     __device__ __forceinline__ void operator()(const AccT& acc, const pg8::Unit& u, int ui, int wr, int wc, int fr, int fq) const {
;         const int row0 = u.pm * 256 + wr * 64 + fr, col0 = u.pn * 128 + wc * 32 + 8 * fq;
;         float rs[2][4]; lane_rstd(lds, ui, wr, fr, rs);
; #pragma unroll
;         for (int ai = 0; ai < 2; ++ai)
; #pragma unroll
;             for (int m = 0; m < 4; ++m) {
;                 const float s = rs[ai][m]; u16* op = act + (size_t)(row0 + ai * 128 + m * 16) * FF + col0;
;                 const float c1 = -1.4426950408889634f * s, c2 = s * s;
;                 u32x4 w;
; #pragma unroll
;                 for (int n = 0; n < 2; ++n)
; #pragma unroll
;                     for (int hh = 0; hh < 2; ++hh) {
;                         const f32x2 ga = {acc[ai][0][m][n][2 * hh], acc[ai][0][m][n][2 * hh + 1]}, ua = {acc[ai][1][m][n][2 * hh], acc[ai][1][m][n][2 * hh + 1]};
;                         f32x2 t = ga * c1; t.x = fminf(t.x, 60.0f); t.y = fminf(t.y, 60.0f);
;                         f32x2 e; e.x = __builtin_amdgcn_exp2f(t.x); e.y = __builtin_amdgcn_exp2f(t.y);
;                         const f32x2 d = e + 1.0f;
;                         const float rp = __builtin_amdgcn_rcpf(d.x * d.y);
;                         const f32x2 r = {d.y * rp, d.x * rp};
;                         const f32x2 o = ((ga * ua) * c2) * r;
;                         w[2 * n + hh] = pk2(o.x, o.y);
;                     }
;                 st16_wt(op, w);
;             }
.Lpeel_gu_after:
	s_and_b64 vcc, exec, s[10:11]
	s_cbranch_vccz .LBB0_215
	s_barrier
.LBB0_215:
	v_and_b32_e32 v141, 15, v234
	s_lshl_b32 s12, s71, 8
	s_add_i32 s12, s12, s56
	v_or_b32_e32 v150, s12, v141
	s_lshl_b32 s12, s62, 7
	v_lshrrev_b32_e32 v140, 1, v234
	v_and_or_b32 v140, v140, 24, s12
	v_or_b32_e32 v152, s57, v140
	s_lshl_b32 s12, s70, 10
	s_add_i32 s12, s60, s12
	v_lshl_add_u32 v140, v141, 2, s12
	ds_read2_b32 v[194:195], v140 offset1:16
	ds_read2_b32 v[196:197], v140 offset0:32 offset1:48
	ds_read2_b32 v[198:199], v140 offset0:128 offset1:144
	ds_read2_b32 v[200:201], v140 offset0:160 offset1:176
	v_ashrrev_i32_e32 v153, 31, v152
	v_mov_b64_e32 v[142:143], s[8:9]
	v_mad_i64_i32 v[156:157], s[12:13], v150, s37, v[142:143]
	v_lshlrev_b64 v[152:153], 1, v[152:153]
	s_mov_b32 s12, 0xb0000
	s_mov_b32 s13, 0
	v_lshl_add_u64 v[156:157], v[156:157], 0, v[152:153]
	v_lshl_add_u64 v[154:155], v[156:157], 0, s[12:13]
	s_mov_b32 s12, 0x16000
	s_andn2_b64 vcc, exec, s[6:7]
	s_waitcnt lgkmcnt(0)
	v_mul_f32_e32 v158, 0xbfb8aa3b, v194
	v_mul_f32_e32 v161, v194, v194
	v_rcp_f32_e32 v160, v161
	v_pk_mul_f32 v[162:163], v[122:123], v[158:159] op_sel_hi:[1,0]
	v_pk_mul_f32 v[164:165], v[124:125], v[158:159] op_sel_hi:[1,0]
	v_pk_mul_f32 v[166:167], v[114:115], v[158:159] op_sel_hi:[1,0]
	v_pk_mul_f32 v[168:169], v[116:117], v[158:159] op_sel_hi:[1,0]
	v_exp_f32_e32 v162, v162
	v_exp_f32_e32 v163, v163
	v_exp_f32_e32 v164, v164
	v_exp_f32_e32 v165, v165
	v_exp_f32_e32 v166, v166
	v_exp_f32_e32 v167, v167
	v_exp_f32_e32 v168, v168
	v_exp_f32_e32 v169, v169
	v_pk_fma_f32 v[162:163], v[162:163], v[160:161], v[160:161] op_sel_hi:[1,0,0]
	v_pk_fma_f32 v[164:165], v[164:165], v[160:161], v[160:161] op_sel_hi:[1,0,0]
	v_pk_fma_f32 v[166:167], v[166:167], v[160:161], v[160:161] op_sel_hi:[1,0,0]
	v_pk_fma_f32 v[168:169], v[168:169], v[160:161], v[160:161] op_sel_hi:[1,0,0]
	v_pk_mul_f32 v[122:123], v[122:123], v[126:127]
	v_pk_mul_f32 v[124:125], v[124:125], v[128:129]
	v_pk_mul_f32 v[114:115], v[114:115], v[118:119]
	v_pk_mul_f32 v[116:117], v[116:117], v[120:121]
	v_rcp_f32_e32 v162, v162
	v_rcp_f32_e32 v163, v163
	v_rcp_f32_e32 v164, v164
	v_rcp_f32_e32 v165, v165
	v_rcp_f32_e32 v166, v166
	v_rcp_f32_e32 v167, v167
	v_rcp_f32_e32 v168, v168
	v_rcp_f32_e32 v169, v169
	s_nop 0
	v_pk_mul_f32 v[122:123], v[122:123], v[162:163]
	v_pk_mul_f32 v[124:125], v[124:125], v[164:165]
	v_pk_mul_f32 v[114:115], v[114:115], v[166:167]
	v_pk_mul_f32 v[116:117], v[116:117], v[168:169]
	v_cvt_pk_bf16_f32 v170, v122, v123
	v_cvt_pk_bf16_f32 v171, v124, v125
	v_cvt_pk_bf16_f32 v172, v114, v115
	v_cvt_pk_bf16_f32 v173, v116, v117
	global_store_dwordx4 v[156:157], v[170:173], off sc1
	s_nop 1
	v_lshl_add_u64 v[156:157], v[156:157], 0, s[12:13]
	v_mul_f32_e32 v158, 0xbfb8aa3b, v195
	v_mul_f32_e32 v161, v195, v195
	v_rcp_f32_e32 v160, v161
	v_pk_mul_f32 v[162:163], v[106:107], v[158:159] op_sel_hi:[1,0]
	v_pk_mul_f32 v[164:165], v[108:109], v[158:159] op_sel_hi:[1,0]
	v_pk_mul_f32 v[166:167], v[98:99], v[158:159] op_sel_hi:[1,0]
	v_pk_mul_f32 v[168:169], v[100:101], v[158:159] op_sel_hi:[1,0]
	v_exp_f32_e32 v162, v162
	v_exp_f32_e32 v163, v163
	v_exp_f32_e32 v164, v164
	v_exp_f32_e32 v165, v165
	v_exp_f32_e32 v166, v166
	v_exp_f32_e32 v167, v167
	v_exp_f32_e32 v168, v168
	v_exp_f32_e32 v169, v169
	v_pk_fma_f32 v[162:163], v[162:163], v[160:161], v[160:161] op_sel_hi:[1,0,0]
	v_pk_fma_f32 v[164:165], v[164:165], v[160:161], v[160:161] op_sel_hi:[1,0,0]
	v_pk_fma_f32 v[166:167], v[166:167], v[160:161], v[160:161] op_sel_hi:[1,0,0]
	v_pk_fma_f32 v[168:169], v[168:169], v[160:161], v[160:161] op_sel_hi:[1,0,0]
	v_pk_mul_f32 v[106:107], v[106:107], v[110:111]
	v_pk_mul_f32 v[108:109], v[108:109], v[112:113]
	v_pk_mul_f32 v[98:99], v[98:99], v[102:103]
	v_pk_mul_f32 v[100:101], v[100:101], v[104:105]
	v_rcp_f32_e32 v162, v162
	v_rcp_f32_e32 v163, v163
	v_rcp_f32_e32 v164, v164
	v_rcp_f32_e32 v165, v165
	v_rcp_f32_e32 v166, v166
	v_rcp_f32_e32 v167, v167
	v_rcp_f32_e32 v168, v168
	v_rcp_f32_e32 v169, v169
	s_nop 0
	v_pk_mul_f32 v[106:107], v[106:107], v[162:163]
	v_pk_mul_f32 v[108:109], v[108:109], v[164:165]
	v_pk_mul_f32 v[98:99], v[98:99], v[166:167]
	v_pk_mul_f32 v[100:101], v[100:101], v[168:169]
	v_cvt_pk_bf16_f32 v174, v106, v107
	v_cvt_pk_bf16_f32 v175, v108, v109
	v_cvt_pk_bf16_f32 v176, v98, v99
	v_cvt_pk_bf16_f32 v177, v100, v101
	global_store_dwordx4 v[156:157], v[174:177], off sc1
	s_nop 1
	v_lshl_add_u64 v[156:157], v[156:157], 0, s[12:13]
	v_mul_f32_e32 v158, 0xbfb8aa3b, v196
	v_mul_f32_e32 v161, v196, v196
	v_rcp_f32_e32 v160, v161
	v_pk_mul_f32 v[162:163], v[90:91], v[158:159] op_sel_hi:[1,0]
	v_pk_mul_f32 v[164:165], v[92:93], v[158:159] op_sel_hi:[1,0]
	v_pk_mul_f32 v[166:167], v[82:83], v[158:159] op_sel_hi:[1,0]
	v_pk_mul_f32 v[168:169], v[84:85], v[158:159] op_sel_hi:[1,0]
	v_exp_f32_e32 v162, v162
	v_exp_f32_e32 v163, v163
	v_exp_f32_e32 v164, v164
	v_exp_f32_e32 v165, v165
	v_exp_f32_e32 v166, v166
	v_exp_f32_e32 v167, v167
	v_exp_f32_e32 v168, v168
	v_exp_f32_e32 v169, v169
	v_pk_fma_f32 v[162:163], v[162:163], v[160:161], v[160:161] op_sel_hi:[1,0,0]
	v_pk_fma_f32 v[164:165], v[164:165], v[160:161], v[160:161] op_sel_hi:[1,0,0]
	v_pk_fma_f32 v[166:167], v[166:167], v[160:161], v[160:161] op_sel_hi:[1,0,0]
	v_pk_fma_f32 v[168:169], v[168:169], v[160:161], v[160:161] op_sel_hi:[1,0,0]
	v_pk_mul_f32 v[90:91], v[90:91], v[94:95]
	v_pk_mul_f32 v[92:93], v[92:93], v[96:97]
	v_pk_mul_f32 v[82:83], v[82:83], v[86:87]
	v_pk_mul_f32 v[84:85], v[84:85], v[88:89]
	v_rcp_f32_e32 v162, v162
	v_rcp_f32_e32 v163, v163
	v_rcp_f32_e32 v164, v164
	v_rcp_f32_e32 v165, v165
; __device__ __forceinline__ unsigned pk2(float lo, float hi) { unsigned r; asm("v_cvt_pk_bf16_f32 %0, %1, %2" : "=v"(r) : "v"(lo), "v"(hi)); return r; }
; __device__ __forceinline__ void st16_wt(void* p, u32x4 v) { asm volatile("global_store_dwordx4 %0, %1, off sc1\n\ts_nop 1" :: "v"(p), "v"(v) : "memory"); }
;     __device__ __forceinline__ void operator()(const AccT& acc, const pg8::Unit& u, int ui, int wr, int wc, int fr, int fq) const {
;     ...
;             for (int m = 0; m < 4; ++m) {
;                 const float s = rs[ai][m]; u16* op = act + (size_t)(row0 + ai * 128 + m * 16) * FF + col0;
;                 const float c1 = -1.4426950408889634f * s, c2 = s * s;
;                 u32x4 w;
; #pragma unroll
;                 for (int n = 0; n < 2; ++n)
; #pragma unroll
;                     for (int hh = 0; hh < 2; ++hh) {
;                         const f32x2 ga = {acc[ai][0][m][n][2 * hh], acc[ai][0][m][n][2 * hh + 1]}, ua = {acc[ai][1][m][n][2 * hh], acc[ai][1][m][n][2 * hh + 1]};
;                         f32x2 t = ga * c1; t.x = fminf(t.x, 60.0f); t.y = fminf(t.y, 60.0f);
;                         f32x2 e; e.x = __builtin_amdgcn_exp2f(t.x); e.y = __builtin_amdgcn_exp2f(t.y);
;                         const f32x2 d = e + 1.0f;
;                         const float rp = __builtin_amdgcn_rcpf(d.x * d.y);
;                         const f32x2 r = {d.y * rp, d.x * rp};
;                         const f32x2 o = ((ga * ua) * c2) * r;
;                         w[2 * n + hh] = pk2(o.x, o.y);
;                     }
;                 st16_wt(op, w);
;             }
	v_rcp_f32_e32 v166, v166
	v_rcp_f32_e32 v167, v167
	v_rcp_f32_e32 v168, v168
	v_rcp_f32_e32 v169, v169
	s_nop 0
	v_pk_mul_f32 v[90:91], v[90:91], v[162:163]
	v_pk_mul_f32 v[92:93], v[92:93], v[164:165]
	v_pk_mul_f32 v[82:83], v[82:83], v[166:167]
	v_pk_mul_f32 v[84:85], v[84:85], v[168:169]
	v_cvt_pk_bf16_f32 v170, v90, v91
	v_cvt_pk_bf16_f32 v171, v92, v93
	v_cvt_pk_bf16_f32 v172, v82, v83
	v_cvt_pk_bf16_f32 v173, v84, v85
	global_store_dwordx4 v[156:157], v[170:173], off sc1
	s_nop 1
	v_lshl_add_u64 v[156:157], v[156:157], 0, s[12:13]
	v_mul_f32_e32 v158, 0xbfb8aa3b, v197
	v_mul_f32_e32 v161, v197, v197
	v_rcp_f32_e32 v160, v161
	v_pk_mul_f32 v[162:163], v[74:75], v[158:159] op_sel_hi:[1,0]
	v_pk_mul_f32 v[164:165], v[76:77], v[158:159] op_sel_hi:[1,0]
	v_pk_mul_f32 v[166:167], v[66:67], v[158:159] op_sel_hi:[1,0]
	v_pk_mul_f32 v[168:169], v[68:69], v[158:159] op_sel_hi:[1,0]
	v_exp_f32_e32 v162, v162
	v_exp_f32_e32 v163, v163
	v_exp_f32_e32 v164, v164
	v_exp_f32_e32 v165, v165
	v_exp_f32_e32 v166, v166
	v_exp_f32_e32 v167, v167
	v_exp_f32_e32 v168, v168
	v_exp_f32_e32 v169, v169
	v_pk_fma_f32 v[162:163], v[162:163], v[160:161], v[160:161] op_sel_hi:[1,0,0]
	v_pk_fma_f32 v[164:165], v[164:165], v[160:161], v[160:161] op_sel_hi:[1,0,0]
	v_pk_fma_f32 v[166:167], v[166:167], v[160:161], v[160:161] op_sel_hi:[1,0,0]
	v_pk_fma_f32 v[168:169], v[168:169], v[160:161], v[160:161] op_sel_hi:[1,0,0]
	v_pk_mul_f32 v[74:75], v[74:75], v[78:79]
	v_pk_mul_f32 v[76:77], v[76:77], v[80:81]
	v_pk_mul_f32 v[66:67], v[66:67], v[70:71]
	v_pk_mul_f32 v[68:69], v[68:69], v[72:73]
	v_rcp_f32_e32 v162, v162
	v_rcp_f32_e32 v163, v163
	v_rcp_f32_e32 v164, v164
	v_rcp_f32_e32 v165, v165
	v_rcp_f32_e32 v166, v166
	v_rcp_f32_e32 v167, v167
	v_rcp_f32_e32 v168, v168
	v_rcp_f32_e32 v169, v169
	s_nop 0
	v_pk_mul_f32 v[74:75], v[74:75], v[162:163]
	v_pk_mul_f32 v[76:77], v[76:77], v[164:165]
	v_pk_mul_f32 v[66:67], v[66:67], v[166:167]
	v_pk_mul_f32 v[68:69], v[68:69], v[168:169]
	v_cvt_pk_bf16_f32 v174, v74, v75
	v_cvt_pk_bf16_f32 v175, v76, v77
	v_cvt_pk_bf16_f32 v176, v66, v67
	v_cvt_pk_bf16_f32 v177, v68, v69
	global_store_dwordx4 v[156:157], v[174:177], off sc1
	s_nop 1
	v_mul_f32_e32 v158, 0xbfb8aa3b, v198
	v_mul_f32_e32 v161, v198, v198
	v_rcp_f32_e32 v160, v161
	v_pk_mul_f32 v[162:163], v[58:59], v[158:159] op_sel_hi:[1,0]
	v_pk_mul_f32 v[164:165], v[60:61], v[158:159] op_sel_hi:[1,0]
	v_pk_mul_f32 v[166:167], v[50:51], v[158:159] op_sel_hi:[1,0]
	v_pk_mul_f32 v[168:169], v[52:53], v[158:159] op_sel_hi:[1,0]
	v_exp_f32_e32 v162, v162
	v_exp_f32_e32 v163, v163
	v_exp_f32_e32 v164, v164
	v_exp_f32_e32 v165, v165
	v_exp_f32_e32 v166, v166
	v_exp_f32_e32 v167, v167
	v_exp_f32_e32 v168, v168
	v_exp_f32_e32 v169, v169
	v_pk_fma_f32 v[162:163], v[162:163], v[160:161], v[160:161] op_sel_hi:[1,0,0]
	v_pk_fma_f32 v[164:165], v[164:165], v[160:161], v[160:161] op_sel_hi:[1,0,0]
	v_pk_fma_f32 v[166:167], v[166:167], v[160:161], v[160:161] op_sel_hi:[1,0,0]
	v_pk_fma_f32 v[168:169], v[168:169], v[160:161], v[160:161] op_sel_hi:[1,0,0]
	v_pk_mul_f32 v[58:59], v[58:59], v[62:63]
	v_pk_mul_f32 v[60:61], v[60:61], v[64:65]
	v_pk_mul_f32 v[50:51], v[50:51], v[54:55]
	v_pk_mul_f32 v[52:53], v[52:53], v[56:57]
	v_rcp_f32_e32 v162, v162
	v_rcp_f32_e32 v163, v163
	v_rcp_f32_e32 v164, v164
	v_rcp_f32_e32 v165, v165
	v_rcp_f32_e32 v166, v166
	v_rcp_f32_e32 v167, v167
	v_rcp_f32_e32 v168, v168
	v_rcp_f32_e32 v169, v169
	s_nop 0
	v_pk_mul_f32 v[58:59], v[58:59], v[162:163]
	v_pk_mul_f32 v[60:61], v[60:61], v[164:165]
	v_pk_mul_f32 v[50:51], v[50:51], v[166:167]
	v_pk_mul_f32 v[52:53], v[52:53], v[168:169]
	v_cvt_pk_bf16_f32 v170, v58, v59
	v_cvt_pk_bf16_f32 v171, v60, v61
	v_cvt_pk_bf16_f32 v172, v50, v51
	v_cvt_pk_bf16_f32 v173, v52, v53
	global_store_dwordx4 v[154:155], v[170:173], off sc1
	s_nop 1
	v_lshl_add_u64 v[154:155], v[154:155], 0, s[12:13]
	v_mul_f32_e32 v158, 0xbfb8aa3b, v199
	v_mul_f32_e32 v161, v199, v199
	v_rcp_f32_e32 v160, v161
	v_pk_mul_f32 v[162:163], v[42:43], v[158:159] op_sel_hi:[1,0]
	v_pk_mul_f32 v[164:165], v[44:45], v[158:159] op_sel_hi:[1,0]
	v_pk_mul_f32 v[166:167], v[34:35], v[158:159] op_sel_hi:[1,0]
	v_pk_mul_f32 v[168:169], v[36:37], v[158:159] op_sel_hi:[1,0]
	v_exp_f32_e32 v162, v162
	v_exp_f32_e32 v163, v163
	v_exp_f32_e32 v164, v164
	v_exp_f32_e32 v165, v165
	v_exp_f32_e32 v166, v166
	v_exp_f32_e32 v167, v167
	v_exp_f32_e32 v168, v168
	v_exp_f32_e32 v169, v169
	v_pk_fma_f32 v[162:163], v[162:163], v[160:161], v[160:161] op_sel_hi:[1,0,0]
; __device__ __forceinline__ unsigned pk2(float lo, float hi) { unsigned r; asm("v_cvt_pk_bf16_f32 %0, %1, %2" : "=v"(r) : "v"(lo), "v"(hi)); return r; }
; __device__ __forceinline__ void st16_wt(void* p, u32x4 v) { asm volatile("global_store_dwordx4 %0, %1, off sc1\n\ts_nop 1" :: "v"(p), "v"(v) : "memory"); }
; #define PG8_BAR __builtin_amdgcn_s_barrier()
; template <class Epi, class Pre, bool AG = false>
; __device__ __forceinline__ void gemm_phase(LAS unsigned char* lds, const Gemm g, const StaticOrder& S, const Epi& E, const Pre& P) {
;     ...
;         if (!has_next) break;
; #pragma unroll
;         for (int a = 0; a < 2; ++a)
; #pragma unroll
;             for (int b = 0; b < 2; ++b)
; #pragma unroll
;                 for (int m = 0; m < 4; ++m)
; #pragma unroll
;                     for (int n = 0; n < 2; ++n) acc[a][b][m][n] = (f32x4){0.f, 0.f, 0.f, 0.f};
;         cur = nxt; cA = nA; cB = nB; ++ui;
;         if (wr == 1) PG8_BAR;
;     }
;     __device__ __forceinline__ void operator()(const AccT& acc, const pg8::Unit& u, int ui, int wr, int wc, int fr, int fq) const {
;     ...
;             for (int m = 0; m < 4; ++m) {
;                 const float s = rs[ai][m]; u16* op = act + (size_t)(row0 + ai * 128 + m * 16) * FF + col0;
;                 const float c1 = -1.4426950408889634f * s, c2 = s * s;
;                 u32x4 w;
; #pragma unroll
;                 for (int n = 0; n < 2; ++n)
; #pragma unroll
;                     for (int hh = 0; hh < 2; ++hh) {
;                         const f32x2 ga = {acc[ai][0][m][n][2 * hh], acc[ai][0][m][n][2 * hh + 1]}, ua = {acc[ai][1][m][n][2 * hh], acc[ai][1][m][n][2 * hh + 1]};
;                         f32x2 t = ga * c1; t.x = fminf(t.x, 60.0f); t.y = fminf(t.y, 60.0f);
;                         f32x2 e; e.x = __builtin_amdgcn_exp2f(t.x); e.y = __builtin_amdgcn_exp2f(t.y);
;                         const f32x2 d = e + 1.0f;
;                         const float rp = __builtin_amdgcn_rcpf(d.x * d.y);
;                         const f32x2 r = {d.y * rp, d.x * rp};
;                         const f32x2 o = ((ga * ua) * c2) * r;
;                         w[2 * n + hh] = pk2(o.x, o.y);
;                     }
;                 st16_wt(op, w);
;             }
	v_pk_fma_f32 v[164:165], v[164:165], v[160:161], v[160:161] op_sel_hi:[1,0,0]
	v_pk_fma_f32 v[166:167], v[166:167], v[160:161], v[160:161] op_sel_hi:[1,0,0]
	v_pk_fma_f32 v[168:169], v[168:169], v[160:161], v[160:161] op_sel_hi:[1,0,0]
	v_pk_mul_f32 v[42:43], v[42:43], v[46:47]
	v_pk_mul_f32 v[44:45], v[44:45], v[48:49]
	v_pk_mul_f32 v[34:35], v[34:35], v[38:39]
	v_pk_mul_f32 v[36:37], v[36:37], v[40:41]
	v_rcp_f32_e32 v162, v162
	v_rcp_f32_e32 v163, v163
	v_rcp_f32_e32 v164, v164
	v_rcp_f32_e32 v165, v165
	v_rcp_f32_e32 v166, v166
	v_rcp_f32_e32 v167, v167
	v_rcp_f32_e32 v168, v168
	v_rcp_f32_e32 v169, v169
	s_nop 0
	v_pk_mul_f32 v[42:43], v[42:43], v[162:163]
	v_pk_mul_f32 v[44:45], v[44:45], v[164:165]
	v_pk_mul_f32 v[34:35], v[34:35], v[166:167]
	v_pk_mul_f32 v[36:37], v[36:37], v[168:169]
	v_cvt_pk_bf16_f32 v174, v42, v43
	v_cvt_pk_bf16_f32 v175, v44, v45
	v_cvt_pk_bf16_f32 v176, v34, v35
	v_cvt_pk_bf16_f32 v177, v36, v37
	global_store_dwordx4 v[154:155], v[174:177], off sc1
	s_nop 1
	v_lshl_add_u64 v[154:155], v[154:155], 0, s[12:13]
	v_mul_f32_e32 v158, 0xbfb8aa3b, v200
	v_mul_f32_e32 v161, v200, v200
	v_rcp_f32_e32 v160, v161
	v_pk_mul_f32 v[162:163], v[26:27], v[158:159] op_sel_hi:[1,0]
	v_pk_mul_f32 v[164:165], v[28:29], v[158:159] op_sel_hi:[1,0]
	v_pk_mul_f32 v[166:167], v[18:19], v[158:159] op_sel_hi:[1,0]
	v_pk_mul_f32 v[168:169], v[20:21], v[158:159] op_sel_hi:[1,0]
	v_exp_f32_e32 v162, v162
	v_exp_f32_e32 v163, v163
	v_exp_f32_e32 v164, v164
	v_exp_f32_e32 v165, v165
	v_exp_f32_e32 v166, v166
	v_exp_f32_e32 v167, v167
	v_exp_f32_e32 v168, v168
	v_exp_f32_e32 v169, v169
	v_pk_fma_f32 v[162:163], v[162:163], v[160:161], v[160:161] op_sel_hi:[1,0,0]
	v_pk_fma_f32 v[164:165], v[164:165], v[160:161], v[160:161] op_sel_hi:[1,0,0]
	v_pk_fma_f32 v[166:167], v[166:167], v[160:161], v[160:161] op_sel_hi:[1,0,0]
	v_pk_fma_f32 v[168:169], v[168:169], v[160:161], v[160:161] op_sel_hi:[1,0,0]
	v_pk_mul_f32 v[26:27], v[26:27], v[30:31]
	v_pk_mul_f32 v[28:29], v[28:29], v[32:33]
	v_pk_mul_f32 v[18:19], v[18:19], v[22:23]
	v_pk_mul_f32 v[20:21], v[20:21], v[24:25]
	v_rcp_f32_e32 v162, v162
	v_rcp_f32_e32 v163, v163
	v_rcp_f32_e32 v164, v164
	v_rcp_f32_e32 v165, v165
	v_rcp_f32_e32 v166, v166
	v_rcp_f32_e32 v167, v167
	v_rcp_f32_e32 v168, v168
	v_rcp_f32_e32 v169, v169
	s_nop 0
	v_pk_mul_f32 v[26:27], v[26:27], v[162:163]
	v_pk_mul_f32 v[28:29], v[28:29], v[164:165]
	v_pk_mul_f32 v[18:19], v[18:19], v[166:167]
	v_pk_mul_f32 v[20:21], v[20:21], v[168:169]
	v_cvt_pk_bf16_f32 v170, v26, v27
	v_cvt_pk_bf16_f32 v171, v28, v29
	v_cvt_pk_bf16_f32 v172, v18, v19
	v_cvt_pk_bf16_f32 v173, v20, v21
	global_store_dwordx4 v[154:155], v[170:173], off sc1
	s_nop 1
	v_lshl_add_u64 v[154:155], v[154:155], 0, s[12:13]
	v_mul_f32_e32 v158, 0xbfb8aa3b, v201
	v_mul_f32_e32 v161, v201, v201
	v_rcp_f32_e32 v160, v161
	v_pk_mul_f32 v[162:163], v[10:11], v[158:159] op_sel_hi:[1,0]
	v_pk_mul_f32 v[164:165], v[12:13], v[158:159] op_sel_hi:[1,0]
	v_pk_mul_f32 v[166:167], v[6:7], v[158:159] op_sel_hi:[1,0]
	v_pk_mul_f32 v[168:169], v[8:9], v[158:159] op_sel_hi:[1,0]
	v_exp_f32_e32 v162, v162
	v_exp_f32_e32 v163, v163
	v_exp_f32_e32 v164, v164
	v_exp_f32_e32 v165, v165
	v_exp_f32_e32 v166, v166
	v_exp_f32_e32 v167, v167
	v_exp_f32_e32 v168, v168
	v_exp_f32_e32 v169, v169
	v_pk_fma_f32 v[162:163], v[162:163], v[160:161], v[160:161] op_sel_hi:[1,0,0]
	v_pk_fma_f32 v[164:165], v[164:165], v[160:161], v[160:161] op_sel_hi:[1,0,0]
	v_pk_fma_f32 v[166:167], v[166:167], v[160:161], v[160:161] op_sel_hi:[1,0,0]
	v_pk_fma_f32 v[168:169], v[168:169], v[160:161], v[160:161] op_sel_hi:[1,0,0]
	v_pk_mul_f32 v[10:11], v[10:11], v[14:15]
	v_pk_mul_f32 v[12:13], v[12:13], v[16:17]
	v_pk_mul_f32 v[6:7], v[6:7], v[2:3]
	v_pk_mul_f32 v[8:9], v[8:9], v[4:5]
	v_rcp_f32_e32 v162, v162
	v_rcp_f32_e32 v163, v163
	v_rcp_f32_e32 v164, v164
	v_rcp_f32_e32 v165, v165
	v_rcp_f32_e32 v166, v166
	v_rcp_f32_e32 v167, v167
	v_rcp_f32_e32 v168, v168
	v_rcp_f32_e32 v169, v169
	s_nop 0
	v_pk_mul_f32 v[10:11], v[10:11], v[162:163]
	v_pk_mul_f32 v[12:13], v[12:13], v[164:165]
	v_pk_mul_f32 v[6:7], v[6:7], v[166:167]
	v_pk_mul_f32 v[8:9], v[8:9], v[168:169]
	v_cvt_pk_bf16_f32 v174, v10, v11
	v_cvt_pk_bf16_f32 v175, v12, v13
	v_cvt_pk_bf16_f32 v176, v6, v7
	v_cvt_pk_bf16_f32 v177, v8, v9
	global_store_dwordx4 v[154:155], v[174:177], off sc1
	s_nop 1
	s_nop 1
	s_mov_b64 s[12:13], -1
	s_cbranch_vccnz .LBB0_208
	s_andn2_b64 vcc, exec, s[0:1]
	s_cbranch_vccnz .LBB0_207
	s_barrier
	s_branch .LBB0_207
